# k49 + POST: dead denormal rescale around v_rsq removed (15 sites), square+sum fused to mul+fmac (14 sites)
# speedup vs baseline: 1.0014x; 1.0014x over previous
; #define LAS __attribute__((address_space(3)))
; DI unsigned pk2(float lo, float hi) { f32x2 x = {lo, hi}; return __builtin_bit_cast(unsigned, __builtin_convertvector(x, bf16x2_t)); }
; DI float sum32(float v) { v += __shfl_xor(v, 16); return sum16(v); }
; DI f32x2 unpk(unsigned w) { f32x2 r = {bflo(w), bfhi(w)}; return r; }
; template <int HP> DI void rope2(f32x2& x, int hl, const LAS f32x2* cs) {
;   const float pa = __shfl_xor(x[0], HP), pb = __shfl_xor(x[1], HP);
;   if (hl < HP) { const f32x2 c0 = cs[2 * hl], c1 = cs[2 * hl + 1]; x[0] = x[0] * c0[0] - pa * c0[1]; x[1] = x[1] * c1[0] - pb * c1[1]; }
;   else if (hl < 2 * HP) { const f32x2 c0 = cs[2 * (hl - HP)], c1 = cs[2 * (hl - HP) + 1]; x[0] = x[0] * c0[0] + pa * c0[1]; x[1] = x[1] * c1[0] + pb * c1[1]; }
; }
; DI void post_unit(const Params& p, int l, int unit, LAS unsigned char* lds) {
;     ...
;   for (int tp = 0; tp < 4; ++tp) {
;     constexpr int segcol[16] = {C_QA, C_QA + 128, C_KA, C_QI, C_QI + 128, C_QI + 256, C_QI + 384, C_KI, C_QB, C_QB + 128, C_KB, C_KB + 128, C_QC, C_QC + 128, C_KC, C_KC + 128};
;     unsigned raw2[2][16];
; #pragma unroll
;     for (int hf = 0; hf < 2; ++hf) { const u16* rowl = proj + (tok0 + w * 8 + 2 * tp + hf) * NP;
; #pragma unroll
;       for (int s = 0; s < 16; ++s) raw2[hf][s] = *(const unsigned*)(rowl + segcol[s] + 2 * lane); }
; #pragma unroll
;     for (int hf = 0; hf < 2; ++hf) {
;     const int t = w * 8 + 2 * tp + hf; u16* row = proj + (tok0 + t) * NP;
; #pragma unroll
;     for (int s = 0; s < 16; ++s) {
;       f32x2 x = unpk(raw2[hf][s]); u16* pp = row + segcol[s] + 2 * lane;
;       if (s < 2) {
;         const float rs = rsqrtf(sum32(x[0] * x[0] + x[1] * x[1]) * (1.0f / 64.0f) + EPS);
;         x[0] *= rs * qna[2 * hl]; x[1] *= rs * qna[2 * hl + 1]; rope2<4>(x, hl, cs16 + t * 8);
;         x *= LOG2E * 0.125f; *(unsigned*)pp = pk2(x[0], x[1]);
.LBB0_150:
	ds_read_b128 v[208:211], v35
	ds_read_b128 v[212:215], v35 offset:64
	ds_read_b128 v[216:219], v39
	ds_read_b128 v[220:223], v39 offset:256
	ds_read_b128 v[224:227], v40
	ds_read_b128 v[228:231], v40 offset:32
	ds_read_b128 v[232:235], v35 offset:128
	ds_read_b128 v[236:239], v39 offset:512
	ds_read_b128 v[240:243], v40 offset:64
	s_waitcnt lgkmcnt(0)
	s_orn2_b64 s[98:99], s[14:15], s[12:13]
	s_orn2_b64 s[100:101], s[8:9], s[6:7]
	v_cndmask_b32_e64 v80, v212, v208, s[12:13]
	v_cndmask_b32_e64 v80, 1.0, v80, s[98:99]
	v_cndmask_b32_e64 v81, v214, v210, s[12:13]
	v_cndmask_b32_e64 v81, 1.0, v81, s[98:99]
	v_cndmask_b32_e64 v82, -v213, v209, s[12:13]
	v_cndmask_b32_e64 v82, 0, v82, s[98:99]
	v_cndmask_b32_e64 v83, -v215, v211, s[12:13]
	v_cndmask_b32_e64 v83, 0, v83, s[98:99]
	v_cndmask_b32_e64 v84, v220, v216, s[10:11]
	v_cndmask_b32_e64 v85, v222, v218, s[10:11]
	v_cndmask_b32_e64 v86, -v221, v217, s[10:11]
	v_cndmask_b32_e64 v87, -v223, v219, s[10:11]
	v_cndmask_b32_e64 v88, v228, v224, s[6:7]
	v_cndmask_b32_e64 v88, 1.0, v88, s[100:101]
	v_cndmask_b32_e64 v89, v230, v226, s[6:7]
	v_cndmask_b32_e64 v89, 1.0, v89, s[100:101]
	v_cndmask_b32_e64 v90, -v229, v225, s[6:7]
	v_cndmask_b32_e64 v90, 0, v90, s[100:101]
	v_cndmask_b32_e64 v91, -v231, v227, s[6:7]
	v_cndmask_b32_e64 v91, 0, v91, s[100:101]
	v_cndmask_b32_e64 v92, v232, v212, s[12:13]
	v_cndmask_b32_e64 v92, 1.0, v92, s[98:99]
	v_cndmask_b32_e64 v93, v234, v214, s[12:13]
	v_cndmask_b32_e64 v93, 1.0, v93, s[98:99]
	v_cndmask_b32_e64 v94, -v233, v213, s[12:13]
	v_cndmask_b32_e64 v94, 0, v94, s[98:99]
	v_cndmask_b32_e64 v95, -v235, v215, s[12:13]
	v_cndmask_b32_e64 v95, 0, v95, s[98:99]
	v_cndmask_b32_e64 v96, v240, v228, s[6:7]
	v_cndmask_b32_e64 v96, 1.0, v96, s[100:101]
	v_cndmask_b32_e64 v97, v242, v230, s[6:7]
	v_cndmask_b32_e64 v97, 1.0, v97, s[100:101]
	v_cndmask_b32_e64 v98, -v241, v229, s[6:7]
	v_cndmask_b32_e64 v98, 0, v98, s[100:101]
	v_cndmask_b32_e64 v99, -v243, v231, s[6:7]
	v_cndmask_b32_e64 v99, 0, v99, s[100:101]
	v_lshl_add_u64 v[18:19], v[12:13], 0, v[0:1]
	v_add_co_u32_e32 v20, vcc, 0xa000000, v18
	s_mov_b32 s2, 0xa001000
	s_waitcnt lgkmcnt(0)
	v_addc_co_u32_e32 v21, vcc, 0, v19, vcc
	global_load_dword v49, v[20:21], off
	v_add_co_u32_e32 v22, vcc, s2, v18
	s_mov_b32 s2, 0xa003000
	s_nop 0
	v_addc_co_u32_e32 v23, vcc, 0, v19, vcc
	v_add_co_u32_e32 v42, vcc, s77, v18
	global_load_dword v59, v[20:21], off offset:512
	global_load_dword v70, v[20:21], off offset:768
	global_load_dword v69, v[20:21], off offset:1024
	global_load_dword v68, v[20:21], off offset:1280
	global_load_dword v67, v[20:21], off offset:1536
	global_load_dword v58, v[20:21], off offset:1792
	global_load_dword v71, v[20:21], off offset:256
	v_addc_co_u32_e32 v43, vcc, 0, v19, vcc
	global_load_dword v56, v[20:21], off offset:2432
	global_load_dword v66, v[20:21], off offset:2688
	global_load_dword v65, v[20:21], off offset:2944
	global_load_dword v64, v[20:21], off offset:3200
	global_load_dword v54, v[22:23], off offset:384
	global_load_dword v63, v[22:23], off offset:640
	global_load_dword v62, v[22:23], off offset:896
	global_load_dword v61, v[22:23], off offset:1152
	v_add_co_u32_e32 v20, vcc, s2, v18
	global_load_dword v60, v[42:43], off offset:512
	global_load_dword v57, v[42:43], off offset:768
	global_load_dword v55, v[42:43], off offset:1024
	global_load_dword v53, v[42:43], off offset:1280
	global_load_dword v52, v[42:43], off offset:1536
	global_load_dword v51, v[42:43], off offset:1792
	global_load_dword v50, v[42:43], off offset:2048
	global_load_dword v48, v[42:43], off offset:2304
	v_addc_co_u32_e32 v21, vcc, 0, v19, vcc
	global_load_dword v47, v[42:43], off offset:2944
	global_load_dword v46, v[42:43], off offset:3200
	global_load_dword v45, v[42:43], off offset:3456
	global_load_dword v44, v[42:43], off offset:3712
	s_nop 0
	global_load_dword v43, v[20:21], off offset:896
	global_load_dword v42, v[20:21], off offset:1152
	global_load_dword v41, v[20:21], off offset:1408
	global_load_dword v3, v[20:21], off offset:1664
	s_waitcnt vmcnt(31)
	v_and_b32_e32 v21, 0xffff0000, v49
	v_lshlrev_b32_e32 v20, 16, v49
	v_mul_f32_e32 v22, v20, v20
	v_fmac_f32_e32 v22, v21, v21
	v_mov_b32_e32 v23, v22
	s_nop 1
	v_permlane16_swap_b32_e32 v22, v23
	v_add_f32_e32 v22, v22, v23
	s_nop 1
	v_add_f32_dpp v22, v22, v22 row_ror:8 row_mask:0xf bank_mask:0xf
	s_nop 1
	v_add_f32_dpp v22, v22, v22 row_ror:4 row_mask:0xf bank_mask:0xf
	s_nop 1
	v_add_f32_dpp v22, v22, v22 quad_perm:[2,3,0,1] row_mask:0xf bank_mask:0xf
	s_nop 1
	v_add_f32_dpp v22, v22, v22 quad_perm:[1,0,3,2] row_mask:0xf bank_mask:0xf
	v_fmamk_f32 v22, v22, 0x3c800000, v170
	v_rsq_f32_e32 v22, v22
	s_nop 0
	v_pk_mul_f32 v[22:23], v[4:5], v[22:23] op_sel_hi:[1,0]
	s_nop 0
	v_pk_mul_f32 v[22:23], v[22:23], v[20:21]
	ds_bpermute_b32 v20, v28, v22
	ds_bpermute_b32 v21, v28, v23
	v_add_u32_e32 v49, 0, v35
	s_waitcnt lgkmcnt(0)
	v_mul_f32_e32 v22, v80, v22
	v_mul_f32_e32 v23, v81, v23
	v_fmac_f32_e32 v22, v82, v20
	v_fmac_f32_e32 v23, v83, v21
	s_mov_b64 s[2:3], 0xa000000
	s_waitcnt lgkmcnt(0)
; #define LAS __attribute__((address_space(3)))
; DI unsigned pk2(float lo, float hi) { f32x2 x = {lo, hi}; return __builtin_bit_cast(unsigned, __builtin_convertvector(x, bf16x2_t)); }
; DI float sum32(float v) { v += __shfl_xor(v, 16); return sum16(v); }
; DI float sum64(float v) { v += __shfl_xor(v, 32); return sum32(v); }
; DI f32x2 unpk(unsigned w) { f32x2 r = {bflo(w), bfhi(w)}; return r; }
; DI void post_unit(const Params& p, int l, int unit, LAS unsigned char* lds) {
;     ...
;     for (int s = 0; s < 16; ++s) {
;       f32x2 x = unpk(raw2[hf][s]); u16* pp = row + segcol[s] + 2 * lane;
;       if (s < 2) {
;         const float rs = rsqrtf(sum32(x[0] * x[0] + x[1] * x[1]) * (1.0f / 64.0f) + EPS);
;         x[0] *= rs * qna[2 * hl]; x[1] *= rs * qna[2 * hl + 1]; rope2<4>(x, hl, cs16 + t * 8);
;         x *= LOG2E * 0.125f; *(unsigned*)pp = pk2(x[0], x[1]);
;       } else if (s == 2) {
;         const float rs = rsqrtf(sum64(x[0] * x[0] + x[1] * x[1]) * (1.0f / 128.0f) + EPS);
;         *(LAS unsigned*)(At + t * 272 + lane * 4) = pk2(x[0] * rs, x[1] * rs);
;       } else if (s < 7) {
;         rope2<4>(x, hl, cs16 + t * 8); *(unsigned*)pp = pk2(x[0], x[1]);
;       } else if (s == 7) {
;         const float rs = rsqrtf(sum32(x[0] * x[0] + x[1] * x[1]) * (1.0f / 64.0f) + EPS);
;         x *= rs; rope2<4>(x, hl, cs16 + t * 8); if (lane < 32) *(unsigned*)((u16*)(p.ws + WS_KIC) + (tok0 + t) * 64 + 2 * lane) = pk2(x[0], x[1]);
	v_lshl_add_u64 v[20:21], v[18:19], 0, s[2:3]
	s_mov_b32 s2, 0x3e38aa3b
	v_pk_mul_f32 v[22:23], v[22:23], s[2:3] op_sel_hi:[1,0]
	s_nop 0
	v_cvt_pk_bf16_f32 v22, v22, v23
	global_store_dword v[20:21], v22, off
	s_waitcnt vmcnt(25)
	v_and_b32_e32 v21, 0xffff0000, v71
	v_lshlrev_b32_e32 v20, 16, v71
	v_mul_f32_e32 v22, v20, v20
	v_fmac_f32_e32 v22, v21, v21
	v_mov_b32_e32 v23, v22
	s_nop 1
	v_permlane16_swap_b32_e32 v22, v23
	v_add_f32_e32 v22, v22, v23
	s_nop 1
	v_add_f32_dpp v22, v22, v22 row_ror:8 row_mask:0xf bank_mask:0xf
	s_nop 1
	v_add_f32_dpp v22, v22, v22 row_ror:4 row_mask:0xf bank_mask:0xf
	s_nop 1
	v_add_f32_dpp v22, v22, v22 quad_perm:[2,3,0,1] row_mask:0xf bank_mask:0xf
	s_nop 1
	v_add_f32_dpp v22, v22, v22 quad_perm:[1,0,3,2] row_mask:0xf bank_mask:0xf
	v_fmamk_f32 v22, v22, 0x3c800000, v170
	v_rsq_f32_e32 v22, v22
	s_nop 0
	v_pk_mul_f32 v[22:23], v[4:5], v[22:23] op_sel_hi:[1,0]
	s_nop 0
	v_pk_mul_f32 v[22:23], v[22:23], v[20:21]
	ds_bpermute_b32 v20, v28, v22
	ds_bpermute_b32 v21, v28, v23
	s_waitcnt lgkmcnt(0)
	v_mul_f32_e32 v22, v80, v22
	v_mul_f32_e32 v23, v81, v23
	v_fmac_f32_e32 v22, v82, v20
	v_fmac_f32_e32 v23, v83, v21
	s_mov_b64 s[2:3], 0xa000100
	s_waitcnt lgkmcnt(0)
	v_lshl_add_u64 v[20:21], v[18:19], 0, s[2:3]
	s_mov_b32 s2, 0x3e38aa3b
	v_pk_mul_f32 v[22:23], v[22:23], s[2:3] op_sel_hi:[1,0]
	s_nop 0
	v_cvt_pk_bf16_f32 v22, v22, v23
	global_store_dword v[20:21], v22, off
	v_lshlrev_b32_e32 v20, 16, v59
	v_and_b32_e32 v21, 0xffff0000, v59
	v_pk_mul_f32 v[22:23], v[20:21], v[20:21]
	v_add_u32_e32 v59, 0, v33
	v_add_f32_e32 v22, v22, v23
	v_mov_b32_e32 v23, v22
	s_nop 1
	v_permlane32_swap_b32_e32 v22, v23
	v_add_f32_e32 v22, v22, v23
	v_mov_b32_e32 v23, v22
	s_nop 1
	v_permlane16_swap_b32_e32 v22, v23
	v_add_f32_e32 v22, v22, v23
	s_nop 1
	v_add_f32_dpp v22, v22, v22 row_ror:8 row_mask:0xf bank_mask:0xf
	s_nop 1
	v_add_f32_dpp v22, v22, v22 row_ror:4 row_mask:0xf bank_mask:0xf
	s_nop 1
	v_add_f32_dpp v22, v22, v22 quad_perm:[2,3,0,1] row_mask:0xf bank_mask:0xf
	s_nop 1
	v_add_f32_dpp v22, v22, v22 quad_perm:[1,0,3,2] row_mask:0xf bank_mask:0xf
	v_fmamk_f32 v22, v22, 0x3c000000, v170
	v_rsq_f32_e32 v22, v22
	s_nop 0
	v_pk_mul_f32 v[20:21], v[22:23], v[20:21] op_sel_hi:[0,1]
	v_cvt_pk_bf16_f32 v20, v20, v21
	ds_write_b32 v59, v20
	v_lshlrev_b32_e32 v20, 16, v70
	v_and_b32_e32 v21, 0xffff0000, v70
	ds_bpermute_b32 v70, v28, v20
	ds_bpermute_b32 v23, v28, v21
	s_waitcnt lgkmcnt(0)
	v_mul_f32_e32 v20, v80, v20
	v_mul_f32_e32 v21, v81, v21
	v_fmac_f32_e32 v20, v82, v70
	v_fmac_f32_e32 v21, v83, v23
	s_mov_b64 s[2:3], 0xa000300
	s_waitcnt lgkmcnt(0)
	v_lshl_add_u64 v[22:23], v[18:19], 0, s[2:3]
	v_cvt_pk_bf16_f32 v20, v20, v21
	global_store_dword v[22:23], v20, off
	v_lshlrev_b32_e32 v20, 16, v69
	v_and_b32_e32 v21, 0xffff0000, v69
	ds_bpermute_b32 v69, v28, v20
	ds_bpermute_b32 v23, v28, v21
	s_waitcnt lgkmcnt(0)
	v_mul_f32_e32 v20, v80, v20
	v_mul_f32_e32 v21, v81, v21
	v_fmac_f32_e32 v20, v82, v69
	v_fmac_f32_e32 v21, v83, v23
	s_mov_b64 s[2:3], 0xa000400
	s_waitcnt lgkmcnt(0)
	v_lshl_add_u64 v[22:23], v[18:19], 0, s[2:3]
	v_cvt_pk_bf16_f32 v20, v20, v21
	global_store_dword v[22:23], v20, off
	v_lshlrev_b32_e32 v20, 16, v68
	v_and_b32_e32 v21, 0xffff0000, v68
	ds_bpermute_b32 v68, v28, v20
	ds_bpermute_b32 v23, v28, v21
	s_waitcnt lgkmcnt(0)
	v_mul_f32_e32 v20, v80, v20
	v_mul_f32_e32 v21, v81, v21
	v_fmac_f32_e32 v20, v82, v68
	v_fmac_f32_e32 v21, v83, v23
	s_mov_b64 s[2:3], 0xa000500
	s_waitcnt lgkmcnt(0)
	v_lshl_add_u64 v[22:23], v[18:19], 0, s[2:3]
	v_cvt_pk_bf16_f32 v20, v20, v21
	global_store_dword v[22:23], v20, off
	v_lshlrev_b32_e32 v20, 16, v67
	v_and_b32_e32 v21, 0xffff0000, v67
	ds_bpermute_b32 v67, v28, v20
	ds_bpermute_b32 v23, v28, v21
	s_waitcnt lgkmcnt(0)
	v_mul_f32_e32 v20, v80, v20
	v_mul_f32_e32 v21, v81, v21
	v_fmac_f32_e32 v20, v82, v67
	v_fmac_f32_e32 v21, v83, v23
	s_mov_b64 s[2:3], 0xa000600
	s_waitcnt lgkmcnt(0)
	v_lshl_add_u64 v[22:23], v[18:19], 0, s[2:3]
	v_cvt_pk_bf16_f32 v20, v20, v21
	global_store_dword v[22:23], v20, off
	v_lshlrev_b32_e32 v20, 16, v58
	v_and_b32_e32 v21, 0xffff0000, v58
	v_mul_f32_e32 v22, v20, v20
	v_fmac_f32_e32 v22, v21, v21
	v_mov_b32_e32 v23, v22
	s_nop 1
	v_permlane16_swap_b32_e32 v22, v23
	v_add_f32_e32 v22, v22, v23
	s_nop 1
	v_add_f32_dpp v22, v22, v22 row_ror:8 row_mask:0xf bank_mask:0xf
	s_nop 1
	v_add_f32_dpp v22, v22, v22 row_ror:4 row_mask:0xf bank_mask:0xf
	s_nop 1
	v_add_f32_dpp v22, v22, v22 quad_perm:[2,3,0,1] row_mask:0xf bank_mask:0xf
	s_nop 1
	v_add_f32_dpp v22, v22, v22 quad_perm:[1,0,3,2] row_mask:0xf bank_mask:0xf
	v_fmamk_f32 v22, v22, 0x3c800000, v170
	v_rsq_f32_e32 v22, v22
	s_nop 0
	v_pk_mul_f32 v[20:21], v[22:23], v[20:21] op_sel_hi:[0,1]
	ds_bpermute_b32 v22, v28, v20
	ds_bpermute_b32 v23, v28, v21
	s_and_saveexec_b64 s[2:3], s[12:13]
	s_xor_b64 s[18:19], exec, s[2:3]
	s_cbranch_execz .LBB0_314
	s_and_saveexec_b64 s[30:31], s[14:15]
	s_cbranch_execz .LBB0_189
	s_waitcnt lgkmcnt(0)
	v_mul_f32_e32 v20, v20, v208
	v_mul_f32_e32 v21, v210, v21
	v_fmac_f32_e32 v20, v209, v22
	v_fmac_f32_e32 v21, v211, v23

; DI unsigned pk2(float lo, float hi) { f32x2 x = {lo, hi}; return __builtin_bit_cast(unsigned, __builtin_convertvector(x, bf16x2_t)); }
; DI float sum16(float v) { v += __shfl_xor(v, 8); v += __shfl_xor(v, 4); v += __shfl_xor(v, 2); v += __shfl_xor(v, 1); return v; }
; DI void post_unit(const Params& p, int l, int unit, LAS unsigned char* lds) {
;     ...
;       } else if (s < 12) {
;         rope2<16>(x, hl, cs64 + t * 32);
;         const int hd = ((s & 1) ? 2 : 0) + hsel;
;         const float lg = log1pf(-exp2f(-5.0f - (float)hd));
;         const float f = (s < 10) ? expf(lg * (float)(t + 1)) : expf(lg * (float)(63 - t)) * 0.125f;
;         x *= f; *(unsigned*)pp = pk2(x[0], x[1]);
;       } else {
;         const float* gn = (s < 14) ? qnc : knc;
;         const float rs = rsqrtf(sum16(x[0] * x[0] + x[1] * x[1]) * (1.0f / 32.0f) + EPS);
;         x[0] *= rs * gn[2 * hl16]; x[1] *= rs * gn[2 * hl16 + 1]; rope2<2>(x, hl16, cs8 + t * 4);
;         if (s < 14) x *= LOG2E * 0.17677669529663687f;
;         *(unsigned*)pp = pk2(x[0], x[1]);
.LBB0_196:
	s_or_b64 exec, exec, s[18:19]
	v_add_u32_e32 v58, s36, v2
	s_waitcnt lgkmcnt(1)
	v_add_u32_e32 v67, 1, v58
	v_cvt_f32_i32_e32 v67, v67
	s_mov_b64 s[2:3], 0xa000980
	s_waitcnt lgkmcnt(0)
	v_lshl_add_u64 v[22:23], v[18:19], 0, s[2:3]
	v_mul_f32_e32 v68, v31, v67
	v_mul_f32_e32 v69, 0x3fb8aa3b, v68
	v_fma_f32 v70, v68, s64, -v69
	v_rndne_f32_e32 v71, v69
	v_fmac_f32_e32 v70, 0x32a5705f, v68
	v_sub_f32_e32 v69, v69, v71
	v_add_f32_e32 v69, v69, v70
	v_exp_f32_e32 v69, v69
	v_cvt_i32_f32_e32 v70, v71
	v_cmp_ngt_f32_e32 vcc, s65, v68
	v_ldexp_f32 v69, v69, v70
	s_nop 0
	v_cndmask_b32_e32 v69, 0, v69, vcc
	v_cmp_nlt_f32_e32 vcc, s89, v68
	s_nop 1
	v_cndmask_b32_e32 v68, v177, v69, vcc
	v_pk_mul_f32 v[20:21], v[68:69], v[20:21] op_sel_hi:[0,1]
	v_cvt_pk_bf16_f32 v20, v20, v21
	global_store_dword v[22:23], v20, off
	s_waitcnt vmcnt(29)
	v_lshlrev_b32_e32 v68, 16, v66
	v_and_b32_e32 v20, 0xffff0000, v66
	ds_bpermute_b32 v66, v26, v68
	ds_bpermute_b32 v21, v26, v20
	s_waitcnt lgkmcnt(0)
	v_mul_f32_e32 v22, v84, v68
	v_mul_f32_e32 v23, v85, v20
	v_fmac_f32_e32 v22, v86, v66
	v_fmac_f32_e32 v23, v87, v21
	s_waitcnt lgkmcnt(1)
	v_mul_f32_e32 v66, v32, v67
	v_mul_f32_e32 v67, 0x3fb8aa3b, v66
	v_fma_f32 v68, v66, s64, -v67
	v_rndne_f32_e32 v69, v67
	v_fmac_f32_e32 v68, 0x32a5705f, v66
	v_sub_f32_e32 v67, v67, v69
	v_add_f32_e32 v67, v67, v68
	v_exp_f32_e32 v67, v67
	v_cvt_i32_f32_e32 v68, v69
	v_cmp_ngt_f32_e32 vcc, s65, v66
	s_mov_b64 s[2:3], 0xa000a80
	s_waitcnt lgkmcnt(0)
	v_lshl_add_u64 v[20:21], v[18:19], 0, s[2:3]
	v_ldexp_f32 v67, v67, v68
	v_cndmask_b32_e32 v67, 0, v67, vcc
	v_cmp_nlt_f32_e32 vcc, s89, v66
	s_nop 1
	v_cndmask_b32_e32 v66, v177, v67, vcc
	v_pk_mul_f32 v[22:23], v[66:67], v[22:23] op_sel_hi:[0,1]
	v_cvt_pk_bf16_f32 v22, v22, v23
	global_store_dword v[20:21], v22, off
	s_waitcnt vmcnt(29)
	v_lshlrev_b32_e32 v66, 16, v65
	v_and_b32_e32 v22, 0xffff0000, v65
	ds_bpermute_b32 v65, v26, v66
	ds_bpermute_b32 v23, v26, v22
	s_waitcnt lgkmcnt(0)
	v_mul_f32_e32 v20, v84, v66
	v_mul_f32_e32 v21, v85, v22
	v_fmac_f32_e32 v20, v86, v65
	v_fmac_f32_e32 v21, v87, v23
	s_waitcnt lgkmcnt(1)
	v_add_u32_e32 v65, 1, v38
	v_cvt_f32_i32_e32 v65, v65
	s_mov_b64 s[2:3], 0xa000b80
	s_waitcnt lgkmcnt(0)
	v_lshl_add_u64 v[22:23], v[18:19], 0, s[2:3]
	v_mul_f32_e32 v66, v31, v65
	v_mul_f32_e32 v67, 0x3fb8aa3b, v66
	v_fma_f32 v68, v66, s64, -v67
	v_rndne_f32_e32 v69, v67
	v_fmac_f32_e32 v68, 0x32a5705f, v66
	v_sub_f32_e32 v67, v67, v69
	v_add_f32_e32 v67, v67, v68
	v_exp_f32_e32 v67, v67
	v_cvt_i32_f32_e32 v68, v69
	v_cmp_ngt_f32_e32 vcc, s65, v66
	v_ldexp_f32 v67, v67, v68
	s_nop 0
	v_cndmask_b32_e32 v67, 0, v67, vcc
	v_cmp_nlt_f32_e32 vcc, s89, v66
	s_nop 1
	v_cndmask_b32_e32 v66, v177, v67, vcc
	v_mul_f32_e32 v66, 0x3e000000, v66
	v_pk_mul_f32 v[20:21], v[66:67], v[20:21] op_sel_hi:[0,1]
	v_cvt_pk_bf16_f32 v20, v20, v21
	global_store_dword v[22:23], v20, off
	s_waitcnt vmcnt(29)
	v_lshlrev_b32_e32 v66, 16, v64
	v_and_b32_e32 v20, 0xffff0000, v64
	ds_bpermute_b32 v64, v26, v66
	ds_bpermute_b32 v21, v26, v20
	s_waitcnt lgkmcnt(0)
	v_mul_f32_e32 v22, v84, v66
	v_mul_f32_e32 v23, v85, v20
	v_fmac_f32_e32 v22, v86, v64
	v_fmac_f32_e32 v23, v87, v21
	s_waitcnt lgkmcnt(1)
	v_mul_f32_e32 v64, v32, v65
	v_mul_f32_e32 v65, 0x3fb8aa3b, v64
	v_fma_f32 v66, v64, s64, -v65
	v_rndne_f32_e32 v67, v65
	v_fmac_f32_e32 v66, 0x32a5705f, v64
	v_sub_f32_e32 v65, v65, v67
	v_add_f32_e32 v65, v65, v66
	v_exp_f32_e32 v65, v65
	v_cvt_i32_f32_e32 v66, v67
	v_cmp_ngt_f32_e32 vcc, s65, v64
	s_mov_b64 s[2:3], 0xa000c80
	s_waitcnt lgkmcnt(0)
	v_lshl_add_u64 v[20:21], v[18:19], 0, s[2:3]
	v_ldexp_f32 v65, v65, v66
	v_cndmask_b32_e32 v65, 0, v65, vcc
	v_cmp_nlt_f32_e32 vcc, s89, v64
	s_nop 1
	v_cndmask_b32_e32 v64, v177, v65, vcc
	v_mul_f32_e32 v64, 0x3e000000, v64
	v_pk_mul_f32 v[22:23], v[64:65], v[22:23] op_sel_hi:[0,1]
	v_cvt_pk_bf16_f32 v22, v22, v23
	global_store_dword v[20:21], v22, off
	s_waitcnt vmcnt(29)
	v_lshlrev_b32_e32 v20, 16, v54
	v_and_b32_e32 v21, 0xffff0000, v54
	v_mul_f32_e32 v22, v20, v20
	v_fmac_f32_e32 v22, v21, v21
	s_nop 1
	v_add_f32_dpp v22, v22, v22 row_ror:8 row_mask:0xf bank_mask:0xf
	s_nop 1
	v_add_f32_dpp v22, v22, v22 row_ror:4 row_mask:0xf bank_mask:0xf
	s_nop 1
	v_add_f32_dpp v22, v22, v22 quad_perm:[2,3,0,1] row_mask:0xf bank_mask:0xf
	s_nop 1
	v_add_f32_dpp v22, v22, v22 quad_perm:[1,0,3,2] row_mask:0xf bank_mask:0xf
	v_fmamk_f32 v22, v22, 0x3d000000, v170
	v_rsq_f32_e32 v22, v22
	s_nop 0
	v_pk_mul_f32 v[22:23], v[6:7], v[22:23] op_sel_hi:[1,0]
	s_nop 0
	v_pk_mul_f32 v[22:23], v[22:23], v[20:21]
	ds_bpermute_b32 v20, v29, v22
	ds_bpermute_b32 v21, v29, v23
	v_add_u32_e32 v54, 0, v40
	s_waitcnt lgkmcnt(0)
	v_mul_f32_e32 v22, v88, v22
	v_mul_f32_e32 v23, v89, v23
	v_fmac_f32_e32 v22, v90, v20
	v_fmac_f32_e32 v23, v91, v21
	s_mov_b64 s[2:3], 0xa001180
	s_waitcnt lgkmcnt(0)
	v_lshl_add_u64 v[20:21], v[18:19], 0, s[2:3]
	s_mov_b32 s2, 0x3e8293ee
	v_pk_mul_f32 v[22:23], v[22:23], s[2:3] op_sel_hi:[1,0]
	s_nop 0
	v_cvt_pk_bf16_f32 v22, v22, v23
	global_store_dword v[20:21], v22, off
	s_waitcnt vmcnt(29)
	v_lshlrev_b32_e32 v20, 16, v63
	v_and_b32_e32 v21, 0xffff0000, v63
	v_mul_f32_e32 v22, v20, v20
	v_fmac_f32_e32 v22, v21, v21
	s_nop 1
	v_add_f32_dpp v22, v22, v22 row_ror:8 row_mask:0xf bank_mask:0xf
	s_nop 1
	v_add_f32_dpp v22, v22, v22 row_ror:4 row_mask:0xf bank_mask:0xf
	s_nop 1
	v_add_f32_dpp v22, v22, v22 quad_perm:[2,3,0,1] row_mask:0xf bank_mask:0xf
	s_nop 1
	v_add_f32_dpp v22, v22, v22 quad_perm:[1,0,3,2] row_mask:0xf bank_mask:0xf
	v_fmamk_f32 v22, v22, 0x3d000000, v170
	v_rsq_f32_e32 v22, v22
	s_nop 0
	v_pk_mul_f32 v[22:23], v[6:7], v[22:23] op_sel_hi:[1,0]
	s_nop 0
	v_pk_mul_f32 v[22:23], v[22:23], v[20:21]
	ds_bpermute_b32 v20, v29, v22
	ds_bpermute_b32 v21, v29, v23
	s_waitcnt lgkmcnt(0)
; #define LAS __attribute__((address_space(3)))
; DI unsigned pk2(float lo, float hi) { f32x2 x = {lo, hi}; return __builtin_bit_cast(unsigned, __builtin_convertvector(x, bf16x2_t)); }
; DI float sum16(float v) { v += __shfl_xor(v, 8); v += __shfl_xor(v, 4); v += __shfl_xor(v, 2); v += __shfl_xor(v, 1); return v; }
; DI float sum32(float v) { v += __shfl_xor(v, 16); return sum16(v); }
; DI float sum64(float v) { v += __shfl_xor(v, 32); return sum32(v); }
; DI f32x2 unpk(unsigned w) { f32x2 r = {bflo(w), bfhi(w)}; return r; }
; DI void post_unit(const Params& p, int l, int unit, LAS unsigned char* lds) {
;     ...
;     for (int s = 0; s < 16; ++s) {
;       f32x2 x = unpk(raw2[hf][s]); u16* pp = row + segcol[s] + 2 * lane;
;       if (s < 2) {
;         const float rs = rsqrtf(sum32(x[0] * x[0] + x[1] * x[1]) * (1.0f / 64.0f) + EPS);
;         x[0] *= rs * qna[2 * hl]; x[1] *= rs * qna[2 * hl + 1]; rope2<4>(x, hl, cs16 + t * 8);
;         x *= LOG2E * 0.125f; *(unsigned*)pp = pk2(x[0], x[1]);
;       } else if (s == 2) {
;         const float rs = rsqrtf(sum64(x[0] * x[0] + x[1] * x[1]) * (1.0f / 128.0f) + EPS);
;         *(LAS unsigned*)(At + t * 272 + lane * 4) = pk2(x[0] * rs, x[1] * rs);
;     ...
;       } else {
;         const float* gn = (s < 14) ? qnc : knc;
;         const float rs = rsqrtf(sum16(x[0] * x[0] + x[1] * x[1]) * (1.0f / 32.0f) + EPS);
;         x[0] *= rs * gn[2 * hl16]; x[1] *= rs * gn[2 * hl16 + 1]; rope2<2>(x, hl16, cs8 + t * 4);
;         if (s < 14) x *= LOG2E * 0.17677669529663687f;
;         *(unsigned*)pp = pk2(x[0], x[1]);
	v_mul_f32_e32 v22, v88, v22
	v_mul_f32_e32 v23, v89, v23
	v_fmac_f32_e32 v22, v90, v20
	v_fmac_f32_e32 v23, v91, v21
	s_mov_b64 s[2:3], 0xa001280
	s_waitcnt lgkmcnt(0)
	v_lshl_add_u64 v[20:21], v[18:19], 0, s[2:3]
	s_mov_b32 s2, 0x3e8293ee
	v_pk_mul_f32 v[22:23], v[22:23], s[2:3] op_sel_hi:[1,0]
	s_nop 0
	v_cvt_pk_bf16_f32 v22, v22, v23
	global_store_dword v[20:21], v22, off
	s_waitcnt vmcnt(29)
	v_lshlrev_b32_e32 v20, 16, v62
	v_and_b32_e32 v21, 0xffff0000, v62
	v_mul_f32_e32 v22, v20, v20
	v_fmac_f32_e32 v22, v21, v21
	s_nop 1
	v_add_f32_dpp v22, v22, v22 row_ror:8 row_mask:0xf bank_mask:0xf
	s_nop 1
	v_add_f32_dpp v22, v22, v22 row_ror:4 row_mask:0xf bank_mask:0xf
	s_nop 1
	v_add_f32_dpp v22, v22, v22 quad_perm:[2,3,0,1] row_mask:0xf bank_mask:0xf
	s_nop 1
	v_add_f32_dpp v22, v22, v22 quad_perm:[1,0,3,2] row_mask:0xf bank_mask:0xf
	v_fmamk_f32 v22, v22, 0x3d000000, v170
	v_rsq_f32_e32 v22, v22
	s_nop 0
	v_pk_mul_f32 v[22:23], v[8:9], v[22:23] op_sel_hi:[1,0]
	s_nop 0
	v_pk_mul_f32 v[22:23], v[22:23], v[20:21]
	ds_bpermute_b32 v20, v29, v22
	ds_bpermute_b32 v21, v29, v23
	s_waitcnt lgkmcnt(0)
	v_mul_f32_e32 v22, v88, v22
	v_mul_f32_e32 v23, v89, v23
	v_fmac_f32_e32 v22, v90, v20
	v_fmac_f32_e32 v23, v91, v21
	s_mov_b64 s[2:3], 0xa001380
	s_waitcnt lgkmcnt(0)
	v_lshl_add_u64 v[20:21], v[18:19], 0, s[2:3]
	v_cvt_pk_bf16_f32 v22, v22, v23
	global_store_dword v[20:21], v22, off
	s_waitcnt vmcnt(29)
	v_lshlrev_b32_e32 v20, 16, v61
	v_and_b32_e32 v21, 0xffff0000, v61
	v_mul_f32_e32 v22, v20, v20
	v_fmac_f32_e32 v22, v21, v21
	s_nop 1
	v_add_f32_dpp v22, v22, v22 row_ror:8 row_mask:0xf bank_mask:0xf
	s_nop 1
	v_add_f32_dpp v22, v22, v22 row_ror:4 row_mask:0xf bank_mask:0xf
	s_nop 1
	v_add_f32_dpp v22, v22, v22 quad_perm:[2,3,0,1] row_mask:0xf bank_mask:0xf
	s_nop 1
	v_add_f32_dpp v22, v22, v22 quad_perm:[1,0,3,2] row_mask:0xf bank_mask:0xf
	v_fmamk_f32 v22, v22, 0x3d000000, v170
	v_rsq_f32_e32 v22, v22
	s_nop 0
	v_pk_mul_f32 v[22:23], v[8:9], v[22:23] op_sel_hi:[1,0]
	s_nop 0
	v_pk_mul_f32 v[22:23], v[22:23], v[20:21]
	ds_bpermute_b32 v20, v29, v22
	ds_bpermute_b32 v21, v29, v23
	s_waitcnt lgkmcnt(0)
	v_mul_f32_e32 v22, v88, v22
	v_mul_f32_e32 v23, v89, v23
	v_fmac_f32_e32 v22, v90, v20
	v_fmac_f32_e32 v23, v91, v21
	s_mov_b64 s[2:3], 0xa001480
	v_lshl_add_u64 v[18:19], v[18:19], 0, s[2:3]
	s_waitcnt lgkmcnt(1)
	v_cvt_pk_bf16_f32 v20, v22, v23
	global_store_dword v[18:19], v20, off
	s_waitcnt vmcnt(29)
	v_and_b32_e32 v19, 0xffff0000, v60
	v_lshlrev_b32_e32 v18, 16, v60
	s_waitcnt lgkmcnt(0)
	v_mul_f32_e32 v20, v18, v18
	v_fmac_f32_e32 v20, v19, v19
	v_mov_b32_e32 v21, v20
	s_nop 1
	v_permlane16_swap_b32_e32 v20, v21
	v_add_f32_e32 v20, v20, v21
	s_nop 1
	v_add_f32_dpp v20, v20, v20 row_ror:8 row_mask:0xf bank_mask:0xf
	s_nop 1
	v_add_f32_dpp v20, v20, v20 row_ror:4 row_mask:0xf bank_mask:0xf
	s_nop 1
	v_add_f32_dpp v20, v20, v20 quad_perm:[2,3,0,1] row_mask:0xf bank_mask:0xf
	s_nop 1
	v_add_f32_dpp v20, v20, v20 quad_perm:[1,0,3,2] row_mask:0xf bank_mask:0xf
	v_fmamk_f32 v20, v20, 0x3c800000, v170
	v_rsq_f32_e32 v20, v20
	s_nop 0
	v_pk_mul_f32 v[20:21], v[4:5], v[20:21] op_sel_hi:[1,0]
	s_nop 0
	v_pk_mul_f32 v[20:21], v[20:21], v[18:19]
	ds_bpermute_b32 v18, v28, v20
	ds_bpermute_b32 v19, v28, v21
	s_waitcnt lgkmcnt(0)
	v_mul_f32_e32 v20, v92, v20
	v_mul_f32_e32 v21, v93, v21
	v_fmac_f32_e32 v20, v94, v18
	v_fmac_f32_e32 v21, v95, v19
	s_mov_b32 s2, 0x3e38aa3b
	s_waitcnt lgkmcnt(0)
	v_lshl_add_u64 v[18:19], v[14:15], 0, v[0:1]
	v_pk_mul_f32 v[20:21], v[20:21], s[2:3] op_sel_hi:[1,0]
	s_nop 0
	v_cvt_pk_bf16_f32 v22, v20, v21
	v_add_co_u32_e32 v20, vcc, 0xa002000, v18
	s_nop 1
	v_addc_co_u32_e32 v21, vcc, 0, v19, vcc
	global_store_dword v[20:21], v22, off offset:512
	s_waitcnt vmcnt(29)
	v_and_b32_e32 v21, 0xffff0000, v57
	v_lshlrev_b32_e32 v20, 16, v57
	v_mul_f32_e32 v22, v20, v20
	v_fmac_f32_e32 v22, v21, v21
	v_mov_b32_e32 v23, v22
	s_nop 1
	v_permlane16_swap_b32_e32 v22, v23
	v_add_f32_e32 v22, v22, v23
	s_nop 1
	v_add_f32_dpp v22, v22, v22 row_ror:8 row_mask:0xf bank_mask:0xf
	s_nop 1
	v_add_f32_dpp v22, v22, v22 row_ror:4 row_mask:0xf bank_mask:0xf
	s_nop 1
	v_add_f32_dpp v22, v22, v22 quad_perm:[2,3,0,1] row_mask:0xf bank_mask:0xf
	s_nop 1
	v_add_f32_dpp v22, v22, v22 quad_perm:[1,0,3,2] row_mask:0xf bank_mask:0xf
	v_fmamk_f32 v22, v22, 0x3c800000, v170
	v_rsq_f32_e32 v22, v22
	s_nop 0
	v_pk_mul_f32 v[22:23], v[4:5], v[22:23] op_sel_hi:[1,0]
	s_nop 0
	v_pk_mul_f32 v[22:23], v[22:23], v[20:21]
	ds_bpermute_b32 v20, v28, v22
	ds_bpermute_b32 v21, v28, v23
	s_waitcnt lgkmcnt(0)
	v_mul_f32_e32 v22, v92, v22
	v_mul_f32_e32 v23, v93, v23
	v_fmac_f32_e32 v22, v94, v20
	v_fmac_f32_e32 v23, v95, v21
	s_mov_b32 s2, 0x3e38aa3b
	s_waitcnt lgkmcnt(0)
	v_pk_mul_f32 v[20:21], v[22:23], s[2:3] op_sel_hi:[1,0]
	s_nop 0
	v_cvt_pk_bf16_f32 v22, v20, v21
	v_add_co_u32_e32 v20, vcc, 0xa002000, v18
	s_nop 1
	v_addc_co_u32_e32 v21, vcc, 0, v19, vcc
	global_store_dword v[20:21], v22, off offset:768
	s_waitcnt vmcnt(29)
	v_lshlrev_b32_e32 v20, 16, v55
	v_and_b32_e32 v21, 0xffff0000, v55
	v_mul_f32_e32 v22, v20, v20
	v_fmac_f32_e32 v22, v21, v21
	v_mov_b32_e32 v23, v22
	s_nop 1
	v_permlane32_swap_b32_e32 v22, v23
	v_add_f32_e32 v22, v22, v23
	v_mov_b32_e32 v23, v22
	s_nop 1
	v_permlane16_swap_b32_e32 v22, v23
	v_add_f32_e32 v22, v22, v23
	s_nop 1
	v_add_f32_dpp v22, v22, v22 row_ror:8 row_mask:0xf bank_mask:0xf
	s_nop 1
	v_add_f32_dpp v22, v22, v22 row_ror:4 row_mask:0xf bank_mask:0xf
	s_nop 1
	v_add_f32_dpp v22, v22, v22 quad_perm:[2,3,0,1] row_mask:0xf bank_mask:0xf
	s_nop 1
	v_add_f32_dpp v22, v22, v22 quad_perm:[1,0,3,2] row_mask:0xf bank_mask:0xf
	v_fmamk_f32 v22, v22, 0x3c000000, v170
	v_rsq_f32_e32 v22, v22
	s_nop 0
	v_pk_mul_f32 v[20:21], v[22:23], v[20:21] op_sel_hi:[0,1]
	v_cvt_pk_bf16_f32 v20, v20, v21
	ds_write_b32 v59, v20 offset:272
	s_waitcnt vmcnt(28)
	v_lshlrev_b32_e32 v20, 16, v53
	v_and_b32_e32 v21, 0xffff0000, v53
	ds_bpermute_b32 v53, v28, v20
	ds_bpermute_b32 v23, v28, v21
	s_waitcnt lgkmcnt(0)
	v_mul_f32_e32 v20, v92, v20
	v_mul_f32_e32 v21, v93, v21
	v_fmac_f32_e32 v20, v94, v53
	v_fmac_f32_e32 v21, v95, v23
	v_cvt_pk_bf16_f32 v22, v20, v21
	v_add_co_u32_e32 v20, vcc, 0xa002000, v18
	s_nop 1
	v_addc_co_u32_e32 v21, vcc, 0, v19, vcc
	global_store_dword v[20:21], v22, off offset:1280
	s_waitcnt vmcnt(28)
	v_lshlrev_b32_e32 v20, 16, v52
	v_and_b32_e32 v21, 0xffff0000, v52
	ds_bpermute_b32 v52, v28, v20
	s_waitcnt lgkmcnt(1)
	ds_bpermute_b32 v23, v28, v21
	s_and_saveexec_b64 s[2:3], s[12:13]
	s_xor_b64 s[18:19], exec, s[2:3]
	s_cbranch_execz .LBB0_254
	s_and_saveexec_b64 s[30:31], s[14:15]
	s_cbranch_execz .LBB0_253
	v_mov_b32_e32 v22, v21
	s_waitcnt lgkmcnt(0)
	v_mul_f32_e32 v20, v212, v20
	v_mul_f32_e32 v21, v214, v22
	v_fmac_f32_e32 v20, v213, v52
	v_fmac_f32_e32 v21, v215, v23

; DI unsigned pk2(float lo, float hi) { f32x2 x = {lo, hi}; return __builtin_bit_cast(unsigned, __builtin_convertvector(x, bf16x2_t)); }
; DI float sum16(float v) { v += __shfl_xor(v, 8); v += __shfl_xor(v, 4); v += __shfl_xor(v, 2); v += __shfl_xor(v, 1); return v; }
; DI void post_unit(const Params& p, int l, int unit, LAS unsigned char* lds) {
;     ...
;       } else {
;         const float* gn = (s < 14) ? qnc : knc;
;         const float rs = rsqrtf(sum16(x[0] * x[0] + x[1] * x[1]) * (1.0f / 32.0f) + EPS);
;         x[0] *= rs * gn[2 * hl16]; x[1] *= rs * gn[2 * hl16 + 1]; rope2<2>(x, hl16, cs8 + t * 4);
;         if (s < 14) x *= LOG2E * 0.17677669529663687f;
;         *(unsigned*)pp = pk2(x[0], x[1]);
.LBB0_296:
	s_or_b64 exec, exec, s[18:19]
	s_mov_b32 s2, 0x3e8293ee
	s_waitcnt lgkmcnt(0)
	v_pk_mul_f32 v[20:21], v[22:23], s[2:3] op_sel_hi:[1,0]
	s_nop 0
	v_cvt_pk_bf16_f32 v22, v20, v21
	v_add_co_u32_e32 v20, vcc, 0xa003000, v18
	s_nop 1
	v_addc_co_u32_e32 v21, vcc, 0, v19, vcc
	global_store_dword v[20:21], v22, off offset:896
	s_waitcnt vmcnt(27)
	v_lshlrev_b32_e32 v20, 16, v42
	v_and_b32_e32 v21, 0xffff0000, v42
	v_mul_f32_e32 v22, v20, v20
	v_fmac_f32_e32 v22, v21, v21
	s_nop 1
	v_add_f32_dpp v22, v22, v22 row_ror:8 row_mask:0xf bank_mask:0xf
	s_nop 1
	v_add_f32_dpp v22, v22, v22 row_ror:4 row_mask:0xf bank_mask:0xf
	s_nop 1
	v_add_f32_dpp v22, v22, v22 quad_perm:[2,3,0,1] row_mask:0xf bank_mask:0xf
	s_nop 1
	v_add_f32_dpp v22, v22, v22 quad_perm:[1,0,3,2] row_mask:0xf bank_mask:0xf
	v_fmamk_f32 v22, v22, 0x3d000000, v170
	v_rsq_f32_e32 v22, v22
	s_nop 0
	v_pk_mul_f32 v[22:23], v[6:7], v[22:23] op_sel_hi:[1,0]
	s_nop 0
	v_pk_mul_f32 v[22:23], v[22:23], v[20:21]
	ds_bpermute_b32 v20, v29, v22
	ds_bpermute_b32 v21, v29, v23
	s_waitcnt lgkmcnt(0)
	v_mul_f32_e32 v22, v96, v22
	v_mul_f32_e32 v23, v97, v23
	v_fmac_f32_e32 v22, v98, v20
	v_fmac_f32_e32 v23, v99, v21
	s_mov_b32 s2, 0x3e8293ee
	s_waitcnt lgkmcnt(0)
	v_pk_mul_f32 v[20:21], v[22:23], s[2:3] op_sel_hi:[1,0]
	s_nop 0
	v_cvt_pk_bf16_f32 v22, v20, v21
	v_add_co_u32_e32 v20, vcc, 0xa003000, v18
	s_nop 1
	v_addc_co_u32_e32 v21, vcc, 0, v19, vcc
	global_store_dword v[20:21], v22, off offset:1152
	s_waitcnt vmcnt(27)
	v_lshlrev_b32_e32 v20, 16, v41
	v_and_b32_e32 v21, 0xffff0000, v41
	v_mul_f32_e32 v22, v20, v20
	v_fmac_f32_e32 v22, v21, v21
	s_nop 1
	v_add_f32_dpp v22, v22, v22 row_ror:8 row_mask:0xf bank_mask:0xf
	s_nop 1
	v_add_f32_dpp v22, v22, v22 row_ror:4 row_mask:0xf bank_mask:0xf
	s_nop 1
	v_add_f32_dpp v22, v22, v22 quad_perm:[2,3,0,1] row_mask:0xf bank_mask:0xf
	s_nop 1
	v_add_f32_dpp v22, v22, v22 quad_perm:[1,0,3,2] row_mask:0xf bank_mask:0xf
	v_fmamk_f32 v22, v22, 0x3d000000, v170
	v_rsq_f32_e32 v22, v22
	s_nop 0
	v_pk_mul_f32 v[22:23], v[8:9], v[22:23] op_sel_hi:[1,0]
	s_nop 0
	v_pk_mul_f32 v[22:23], v[22:23], v[20:21]
	ds_bpermute_b32 v20, v29, v22
	ds_bpermute_b32 v21, v29, v23
	s_waitcnt lgkmcnt(0)
	v_mul_f32_e32 v22, v96, v22
	v_mul_f32_e32 v23, v97, v23
	v_fmac_f32_e32 v22, v98, v20
	v_fmac_f32_e32 v23, v99, v21
	s_waitcnt lgkmcnt(1)
	v_add_co_u32_e32 v20, vcc, 0xa003000, v18
	v_cvt_pk_bf16_f32 v22, v22, v23
	s_waitcnt lgkmcnt(0)
	v_addc_co_u32_e32 v21, vcc, 0, v19, vcc
	global_store_dword v[20:21], v22, off offset:1408
	s_waitcnt vmcnt(27)
	v_lshlrev_b32_e32 v20, 16, v3
	v_and_b32_e32 v21, 0xffff0000, v3
	v_pk_mul_f32 v[22:23], v[20:21], v[20:21]
	s_nop 0
	v_add_f32_e32 v3, v22, v23
	s_nop 1
	v_add_f32_dpp v3, v3, v3 row_ror:8 row_mask:0xf bank_mask:0xf
	s_nop 1
	v_add_f32_dpp v3, v3, v3 row_ror:4 row_mask:0xf bank_mask:0xf
	s_nop 1
	v_add_f32_dpp v3, v3, v3 quad_perm:[2,3,0,1] row_mask:0xf bank_mask:0xf
	s_nop 1
	v_add_f32_dpp v3, v3, v3 quad_perm:[1,0,3,2] row_mask:0xf bank_mask:0xf
	v_fmamk_f32 v3, v3, 0x3d000000, v170
	v_cmp_gt_f32_e32 vcc, s33, v3
	v_mul_f32_e32 v22, 0x4b800000, v3
	s_nop 0
	v_cndmask_b32_e32 v3, v3, v22, vcc
	v_rsq_f32_e32 v3, v3
	s_nop 0
	v_mul_f32_e32 v22, 0x45800000, v3
	v_cndmask_b32_e32 v22, v3, v22, vcc
	v_pk_mul_f32 v[22:23], v[8:9], v[22:23] op_sel_hi:[1,0]
	s_nop 0
	v_pk_mul_f32 v[22:23], v[22:23], v[20:21]
	ds_bpermute_b32 v3, v29, v22
	ds_bpermute_b32 v21, v29, v23
	s_and_saveexec_b64 s[2:3], s[6:7]
	s_xor_b64 s[18:19], exec, s[2:3]
	s_cbranch_execz .LBB0_312
	s_and_saveexec_b64 s[30:31], s[8:9]
	s_cbranch_execz .LBB0_311
	v_mov_b32_e32 v20, v23
	s_waitcnt lgkmcnt(0)
	v_mul_f32_e32 v22, v22, v228
	v_mul_f32_e32 v23, v20, v230
	v_fmac_f32_e32 v22, v229, v3
	v_fmac_f32_e32 v23, v21, v231
